# adds: prefetch address chains in both prompt attention tile loops (v_add_co/s_nop/v_addc, 12 slots per tile) replaced by v_lshl_add_u64 with SGPR-pair constants (3 slots)
# speedup vs baseline: 1.0445x; 1.0037x over previous
; #define ATT_LOAD(S, j) do { rk##S = *(const u32x4*)(ksrc + (size_t)(j) * 64 * 1024); if (!DIFF && tid < 256) rk2##S = *(const u32x4*)(k2src + (size_t)(j) * 64 * 32); \
;         rv0##S = *(const u32x4*)(vsrc + (size_t)(j) * 64 * 1024); if (DIFF) rv1##S = *(const u32x4*)(vsrc + (size_t)(j) * 64 * 1024 + 32 * 1024); } while (0)
; template <bool DIFF>
; __device__ __forceinline__ void attn_unit_coop(const Grp& G, int b, int h, int qb, int n, LAS unsigned char* lds, const int tid_in) {
;     ...
;             if (j + 2 < NT) ATT_LOAD(B, j + 2);
.LBB0_520:
	s_add_i32 s69, s59, 2
	s_cmp_lt_u32 s69, s6
	s_cselect_b64 s[42:43], -1, 0
	s_cmp_ge_u32 s69, s6
	s_cselect_b64 s[40:41], -1, 0
	s_and_b64 vcc, exec, s[40:41]
	v_lshl_add_u64 v[200:201], v[196:197], 0, s[12:13]
	v_lshl_add_u64 v[202:203], v[198:199], 0, s[12:13]
	s_cbranch_vccnz .LBB0_522
	s_mov_b64 vcc, 0x10000
	v_lshl_add_u64 v[80:81], v[202:203], 0, s[96:97]
	global_load_dwordx4 v[140:143], v[80:81], off
	v_lshl_add_u64 v[80:81], v[200:201], 0, s[96:97]
	v_lshl_add_u64 v[82:83], v[80:81], 0, vcc
	global_load_dwordx4 v[144:147], v[80:81], off
	global_load_dwordx4 v[148:151], v[82:83], off

; #define ATT_LOAD(S, j) do { rk##S = *(const u32x4*)(ksrc + (size_t)(j) * 64 * 1024); if (!DIFF && tid < 256) rk2##S = *(const u32x4*)(k2src + (size_t)(j) * 64 * 32); \
;         rv0##S = *(const u32x4*)(vsrc + (size_t)(j) * 64 * 1024); if (DIFF) rv1##S = *(const u32x4*)(vsrc + (size_t)(j) * 64 * 1024 + 32 * 1024); } while (0)
; template <bool DIFF>
; __device__ __forceinline__ void attn_unit_coop(const Grp& G, int b, int h, int qb, int n, LAS unsigned char* lds, const int tid_in) {
;     ...
;             if (j + 3 < NT) ATT_LOAD(A, j + 3);
.LBB0_542:
	s_mov_b64 s[98:99], 0x60000
	s_mov_b64 vcc, 0x10000
	v_lshl_add_u64 v[80:81], v[202:203], 0, s[98:99]
	global_load_dwordx4 v[128:131], v[80:81], off
	v_lshl_add_u64 v[80:81], v[200:201], 0, s[98:99]
	v_lshl_add_u64 v[82:83], v[80:81], 0, vcc
	global_load_dwordx4 v[132:135], v[80:81], off
	global_load_dwordx4 v[136:139], v[82:83], off
	s_cmp_ge_i32 s59, s7
	s_cbranch_scc1 .LBB0_538

; #define ATT_LOAD(S, j) do { rk##S = *(const u32x4*)(ksrc + (size_t)(j) * 64 * 1024); if (!DIFF && tid < 256) rk2##S = *(const u32x4*)(k2src + (size_t)(j) * 64 * 32); \
;         rv0##S = *(const u32x4*)(vsrc + (size_t)(j) * 64 * 1024); if (DIFF) rv1##S = *(const u32x4*)(vsrc + (size_t)(j) * 64 * 1024 + 32 * 1024); } while (0)
; template <bool DIFF>
; __device__ __forceinline__ void attn_unit_coop(const Grp& G, int b, int h, int qb, int n, LAS unsigned char* lds, const int tid_in) {
;     ...
;             if (j + 2 < NT) ATT_LOAD(B, j + 2);
.LBB0_577:
	v_lshl_add_u64 v[48:49], v[150:151], 0, s[96:97]
	global_load_dwordx4 v[116:119], v[48:49], off
	s_and_saveexec_b64 s[4:5], s[0:1]
	s_cbranch_execz .LBB0_579
	v_lshl_add_u64 v[48:49], v[144:145], 0, s[10:11]
	s_mov_b64 vcc, 0x2000
	v_lshl_add_u64 v[48:49], v[48:49], 0, vcc
	global_load_dwordx4 v[120:123], v[48:49], off
.LBB0_579:
	s_or_b64 exec, exec, s[4:5]
	v_lshl_add_u64 v[48:49], v[148:149], 0, s[10:11]
	v_lshl_add_u64 v[48:49], v[48:49], 0, s[96:97]
	global_load_dwordx4 v[124:127], v[48:49], off
	s_cmp_gt_i32 s58, s6
	s_cbranch_scc1 .LBB0_572

; #define ATT_LOAD(S, j) do { rk##S = *(const u32x4*)(ksrc + (size_t)(j) * 64 * 1024); if (!DIFF && tid < 256) rk2##S = *(const u32x4*)(k2src + (size_t)(j) * 64 * 32); \
;         rv0##S = *(const u32x4*)(vsrc + (size_t)(j) * 64 * 1024); if (DIFF) rv1##S = *(const u32x4*)(vsrc + (size_t)(j) * 64 * 1024 + 32 * 1024); } while (0)
; template <bool DIFF>
; __device__ __forceinline__ void attn_unit_coop(const Grp& G, int b, int h, int qb, int n, LAS unsigned char* lds, const int tid_in) {
;     ...
;             if (j + 3 < NT) ATT_LOAD(A, j + 3);
.LBB0_582:
	s_mov_b64 s[98:99], 0x60000
	v_lshl_add_u64 v[48:49], v[150:151], 0, s[98:99]
	global_load_dwordx4 v[108:111], v[48:49], off
	s_and_saveexec_b64 s[4:5], s[0:1]
	s_cbranch_execz .LBB0_584
	v_lshl_add_u64 v[48:49], v[144:145], 0, s[10:11]
	s_mov_b64 vcc, 0x3000
	v_lshl_add_u64 v[48:49], v[48:49], 0, vcc
	global_load_dwordx4 v[104:107], v[48:49], off
.LBB0_584:
	s_or_b64 exec, exec, s[4:5]
	v_lshl_add_u64 v[48:49], v[148:149], 0, s[10:11]
	v_lshl_add_u64 v[48:49], v[48:49], 0, s[98:99]
	global_load_dwordx4 v[112:115], v[48:49], off
	s_cmp_ge_i32 s58, s6
	s_cbranch_scc1 .LBB0_576
